# first barrier (layer 0 weight prep -> in-projection) uses the XCD-hierarchical barrier instead of the cooperative-groups grid sync
# speedup vs baseline: 1.0097x; 1.0028x over previous
; __device__ __forceinline__ void xcd_barrier(const XcdBarrier& b) {
;     asm volatile("s_waitcnt vmcnt(0)" ::: "memory");
;     __syncthreads();
;     if (threadIdx.x == 0) {
;         unsigned* bar = b.bar;
;         __builtin_amdgcn_s_waitcnt(0);
;         unsigned nloc = b.st[0], nx = b.st[1];
;         if (nloc == 0u) { xcd_barrier_complete(bar, b.x, nloc, nx); b.st[0] = nloc; b.st[1] = nx; }
; __global__ void __launch_bounds__(512, 2) mk_fwd(Args args) {
;     ...
;         if (ph == args.ph_lo + 1) cg::this_grid().sync();
;         else if (ph > args.ph_lo) xcd_barrier(bar);
.Lwp_bar:
	v_readlane_b32 s0, v253, 48
	s_cmp_lg_u32 s34, s0
	s_mov_b64 s[0:1], 0
	s_mov_b64 s[18:19], -1
	s_mov_b64 s[18:19], 0
	s_cmp_gt_i32 s34, s58
	s_cbranch_scc0 .LBB0_61
	s_waitcnt vmcnt(0)
	s_barrier
	s_mov_b64 s[20:21], exec
	v_readlane_b32 s0, v254, 41
	v_readlane_b32 s1, v254, 42
	s_and_b64 s[0:1], s[20:21], s[0:1]
	s_mov_b64 exec, s[0:1]
	s_cbranch_execz .LBB0_60
	v_readlane_b32 s0, v254, 39
	s_waitcnt vmcnt(0) expcnt(0) lgkmcnt(0)
	s_nop 0
	v_mov_b32_e32 v0, s0
	ds_read_b32 v3, v0
	v_readlane_b32 s0, v254, 40
	s_waitcnt lgkmcnt(0)
	v_cmp_ne_u32_e32 vcc, 0, v3
	v_mov_b32_e32 v0, s0
	ds_read_b32 v2, v0
	s_cbranch_vccnz .LBB0_28
	v_readlane_b32 s8, v253, 49
	v_readlane_b32 s9, v253, 50
	s_load_dwordx2 s[0:1], s[8:9], 0x0
	s_load_dword s2, s[8:9], 0x8
	s_mov_b32 s12, 1
	s_waitcnt lgkmcnt(0)
	s_mul_i32 s0, s1, s0
	s_mul_i32 s2, s0, s2
	s_branch .LBB0_16
